# attention fast loop: next tile's slot/address setup moved from after the barrier into the previous tile's last PV MFMA gaps (loop-edge edit)
# speedup vs baseline: 1.0032x; 1.0032x over previous
; __device__ __forceinline__ void finishSM_fix(f32x16& p0, f32x16& p1, float& l_lane, bf16x8& pa0, bf16x8& pa1, bf16x8& pa2, bf16x8& pa3) {
; #pragma unroll
;   for (int r = 0; r < 16; ++r) p1[r] = __builtin_amdgcn_exp2f(p1[r]);
;   float ps = 0;
; #pragma unroll
;   for (int r = 0; r < 16; ++r) ps += p0[r];
; #pragma unroll
;   for (int r = 0; r < 16; ++r) ps += p1[r];
;   l_lane += ps;
;     ...
;   PK4(p0, 0, pa0); PK4(p0, 8, pa1); PK4(p1, 0, pa2); PK4(p1, 8, pa3);
;     ...
; }
; __device__ __forceinline__ void qkt12(f32x16& p0, f32x16& p1, const char* Ks, const bf16x8 (&qr)[12], const int (&kb)[4]) {
;   p0 = f32x16{}; p1 = f32x16{};
;     ...
;   bf16x8 c0 = KLD(0, 0), c1 = KLD(0, 1);
; #pragma unroll
;   for (int d0 = 0; d0 < 12; ++d0) {
;     bf16x8 n0 = c0, n1 = c1;
;     if (d0 < 11) { n0 = KLD(d0 + 1, 0); n1 = KLD(d0 + 1, 1); }
;     __builtin_amdgcn_sched_group_barrier(0x100, 2, 0);
;     p0 = __builtin_amdgcn_mfma_f32_32x32x16_bf16(c0, qr[d0], p0, 0, 0, 0);
;     p1 = __builtin_amdgcn_mfma_f32_32x32x16_bf16(c1, qr[d0], p1, 0, 0, 0);
;     __builtin_amdgcn_sched_group_barrier(0x008, 2, 0);
;     c0 = n0; c1 = n1; }
;     ...
; }
.Lfa_entry:
	v_mov_b32_e32 v82, v195
	v_mov_b32_e32 v83, v216
	v_mov_b32_e32 v84, v213
	v_mov_b32_e32 v85, v215
	v_mov_b32_e32 v86, v197
	v_mov_b32_e32 v87, v214
	v_mov_b32_e32 v88, v196
	v_mov_b32_e32 v89, v212
	v_mov_b32_e32 v90, v191
	v_mov_b32_e32 v91, v193
	v_mov_b32_e32 v92, v189
	v_mov_b32_e32 v93, v192
	v_mov_b32_e32 v94, v188
	v_mov_b32_e32 v95, v190
	v_mov_b32_e32 v96, v187
	v_mov_b32_e32 v97, v194
	s_add_i32 s22, s26, 1
	s_cmp_lg_u32 s26, 2
	s_cselect_b32 s24, s22, 0
	s_add_i32 s22, s24, 1
	s_cmp_lg_u32 s24, 2
	s_cselect_b32 s25, s22, 0
	s_mul_i32 s6, s24, 0x6000
	s_mul_i32 s10, s26, 0x6000
	s_lshl_b32 s11, s25, 14
	s_add_i32 s10, s43, s10
	s_add_i32 s11, s52, s11
	v_add_u32_e32 v187, s6, v183
	v_add_u32_e32 v188, s6, v184
	v_add_u32_e32 v189, s6, v185
	v_add_u32_e32 v190, s6, v186
	v_lshl_add_u32 v191, s26, 14, v182
.Lfa_loop:
	s_waitcnt vmcnt(5)
	s_barrier
	ds_read_b128 v[172:175], v187
	ds_read_b128 v[176:179], v187 offset:12288
	ds_read_b128 v[200:203], v188
	ds_read_b128 v[204:207], v188 offset:12288
	v_add_f32_e32 v196, v82, v83
	v_cvt_pk_bf16_f32 v82, v82, v83
	v_add_f32_e32 v197, v84, v85
	v_exp_f32_e32 v66, v66
	v_exp_f32_e32 v67, v67
	v_cvt_pk_bf16_f32 v83, v84, v85
	v_add_f32_e32 v196, v86, v196
	v_add_f32_e32 v197, v87, v197
	s_waitcnt lgkmcnt(3)
	v_mfma_f32_32x32x16_bf16 v[98:113], v[172:175], v[116:119], 0
	v_exp_f32_e32 v68, v68
	v_exp_f32_e32 v69, v69
	s_waitcnt lgkmcnt(2)
	v_mfma_f32_32x32x16_bf16 v[212:227], v[176:179], v[116:119], 0
	ds_read_b128 v[172:175], v189
	ds_read_b128 v[176:179], v189 offset:12288
	v_cvt_pk_bf16_f32 v84, v86, v87
	v_add_f32_e32 v196, v88, v196
	v_add_f32_e32 v197, v89, v197
	v_exp_f32_e32 v70, v70
	s_waitcnt lgkmcnt(3)
	v_mfma_f32_32x32x16_bf16 v[98:113], v[200:203], v[120:123], v[98:113]
	s_mov_b32 m0, s10
	v_lshl_add_u64 v[192:193], v[166:167], 0, s[92:93]
	global_load_lds_dwordx4 v[192:193], off
	v_exp_f32_e32 v71, v71
	s_waitcnt lgkmcnt(2)
	v_mfma_f32_32x32x16_bf16 v[212:227], v[204:207], v[120:123], v[212:227]
	ds_read_b128 v[200:203], v190
	ds_read_b128 v[204:207], v190 offset:12288
	v_cvt_pk_bf16_f32 v85, v88, v89
	v_add_f32_e32 v196, v90, v196
	v_add_f32_e32 v197, v91, v197
	v_exp_f32_e32 v72, v72
	s_waitcnt lgkmcnt(3)
	v_mfma_f32_32x32x16_bf16 v[98:113], v[172:175], v[124:127], v[98:113]
	v_exp_f32_e32 v73, v73
	s_waitcnt lgkmcnt(2)
	v_mfma_f32_32x32x16_bf16 v[212:227], v[176:179], v[124:127], v[212:227]
	ds_read_b128 v[172:175], v187 offset:128
	ds_read_b128 v[176:179], v187 offset:12416
	v_cvt_pk_bf16_f32 v86, v90, v91
	v_add_f32_e32 v196, v92, v196
	v_add_f32_e32 v197, v93, v197
	v_exp_f32_e32 v74, v74
	s_waitcnt lgkmcnt(3)
	v_mfma_f32_32x32x16_bf16 v[98:113], v[200:203], v[128:131], v[98:113]
	s_add_i32 m0, s10, 0x400
	v_lshl_add_u64 v[192:193], v[168:169], 0, s[92:93]
	global_load_lds_dwordx4 v[192:193], off
	v_exp_f32_e32 v75, v75
	v_cvt_pk_bf16_f32 v87, v92, v93
	s_waitcnt lgkmcnt(2)
	v_mfma_f32_32x32x16_bf16 v[212:227], v[204:207], v[128:131], v[212:227]
	ds_read_b128 v[200:203], v188 offset:128
	ds_read_b128 v[204:207], v188 offset:12416
	v_add_f32_e32 v196, v94, v196
	v_add_f32_e32 v197, v95, v197
	v_exp_f32_e32 v76, v76
	s_waitcnt lgkmcnt(3)
	v_mfma_f32_32x32x16_bf16 v[98:113], v[172:175], v[132:135], v[98:113]
	v_exp_f32_e32 v77, v77
	v_cvt_pk_bf16_f32 v88, v94, v95
	s_waitcnt lgkmcnt(2)
	v_mfma_f32_32x32x16_bf16 v[212:227], v[176:179], v[132:135], v[212:227]
	ds_read_b128 v[172:175], v189 offset:128
	ds_read_b128 v[176:179], v189 offset:12416
	v_add_f32_e32 v196, v96, v196
	v_add_f32_e32 v197, v97, v197
	v_exp_f32_e32 v78, v78
	s_waitcnt lgkmcnt(3)
	v_mfma_f32_32x32x16_bf16 v[98:113], v[200:203], v[136:139], v[98:113]
	s_add_i32 m0, s10, 0x800
	v_lshl_add_u64 v[192:193], v[170:171], 0, s[92:93]
	global_load_lds_dwordx4 v[192:193], off
	v_exp_f32_e32 v79, v79
	v_cvt_pk_bf16_f32 v89, v96, v97
	s_waitcnt lgkmcnt(2)
	v_mfma_f32_32x32x16_bf16 v[212:227], v[204:207], v[136:139], v[212:227]
	ds_read_b128 v[200:203], v190 offset:128
	ds_read_b128 v[204:207], v190 offset:12416
	v_exp_f32_e32 v80, v80
	v_exp_f32_e32 v81, v81
	s_waitcnt lgkmcnt(3)
	v_mfma_f32_32x32x16_bf16 v[98:113], v[172:175], v[140:143], v[98:113]
	v_add_f32_e32 v196, v66, v196
	v_add_f32_e32 v197, v67, v197
	v_cvt_pk_bf16_f32 v66, v66, v67
	s_waitcnt lgkmcnt(2)
	v_mfma_f32_32x32x16_bf16 v[212:227], v[176:179], v[140:143], v[212:227]
	ds_read_b128 v[172:175], v187 offset:256
	ds_read_b128 v[176:179], v187 offset:12544
	v_permlane32_swap_b32_e32 v82, v84
	v_permlane32_swap_b32_e32 v83, v85
	v_permlane32_swap_b32_e32 v86, v88
	v_permlane32_swap_b32_e32 v87, v89
	s_waitcnt lgkmcnt(3)
	v_mfma_f32_32x32x16_bf16 v[98:113], v[200:203], v[144:147], v[98:113]
	s_mov_b64 s[22:23], 0x61e0c100
	s_mov_b32 m0, s11
	v_lshl_add_u64 v[192:193], v[164:165], 0, s[22:23]
	global_load_lds_dwordx4 v[192:193], off
	v_add_f32_e32 v196, v68, v196
	v_add_f32_e32 v197, v69, v197
	v_cvt_pk_bf16_f32 v67, v68, v69
	s_waitcnt lgkmcnt(2)
	v_mfma_f32_32x32x16_bf16 v[212:227], v[204:207], v[144:147], v[212:227]
	ds_read_b128 v[200:203], v188 offset:256
	ds_read_b128 v[204:207], v188 offset:12544
	v_add_f32_e32 v196, v70, v196
	v_add_f32_e32 v197, v71, v197
	v_cvt_pk_bf16_f32 v68, v70, v71
	v_add_f32_e32 v196, v72, v196
	s_waitcnt lgkmcnt(3)
	v_mfma_f32_32x32x16_bf16 v[98:113], v[172:175], v[152:155], v[98:113]
	ds_read_b64_tr_b16 v[228:229], v191 offset:0
	ds_read_b64_tr_b16 v[230:231], v191 offset:2048
	v_add_f32_e32 v197, v73, v197
	v_cvt_pk_bf16_f32 v69, v72, v73
	v_add_f32_e32 v196, v74, v196
	v_add_f32_e32 v197, v75, v197
	s_waitcnt lgkmcnt(4)
; #define SBAR() __builtin_amdgcn_sched_barrier(0)
; #define KDMA(t, slot) do { const char* g_ = (const char*)Kh + (size_t)(t) * (KVBLK * LDK * 2); _Pragma("unroll") for (int i_ = 0; i_ < 3; ++i_) \
;     __builtin_amdgcn_global_load_lds((const unsigned*)(g_ + kdo[i_]), (LAS unsigned*)(ldsl + DMA_KRING + (slot) * SHM_K + (wid * 3 + i_) * 1024), 16, 0, 0); } while (0)
; template <int D0> __device__ __forceinline__ void pv_one(f32x16& od, int vb, bf16x8 pa0, bf16x8 pa1, bf16x8 pa2, bf16x8 pa3) {
;   const s16x4 l0 = tr_read<v_rd_off(D0, 0, 0)>(vb), h0 = tr_read<v_rd_off(D0, 0, 1)>(vb), l1 = tr_read<v_rd_off(D0, 1, 0)>(vb), h1 = tr_read<v_rd_off(D0, 1, 1)>(vb);
;   const s16x4 l2 = tr_read<v_rd_off(D0, 2, 0)>(vb), h2 = tr_read<v_rd_off(D0, 2, 1)>(vb), l3 = tr_read<v_rd_off(D0, 3, 0)>(vb), h3 = tr_read<v_rd_off(D0, 3, 1)>(vb);
;   asm volatile("s_waitcnt lgkmcnt(0)" ::: "memory"); SBAR();
;     ...
;   od = __builtin_amdgcn_mfma_f32_32x32x16_bf16(pa0, PK(l0, h0), od, 0, 0, 0);
;   od = __builtin_amdgcn_mfma_f32_32x32x16_bf16(pa1, PK(l1, h1), od, 0, 0, 0);
;   od = __builtin_amdgcn_mfma_f32_32x32x16_bf16(pa2, PK(l2, h2), od, 0, 0, 0);
;   od = __builtin_amdgcn_mfma_f32_32x32x16_bf16(pa3, PK(l3, h3), od, 0, 0, 0);
;     ...
; }
; __device__ __forceinline__ void pv_d0(f32x16 (&o)[4], int vb, bf16x8 pa0, bf16x8 pa1, bf16x8 pa2, bf16x8 pa3) {
;   pv_one<0>(o[0], vb, pa0, pa1, pa2, pa3); pv_one<1>(o[1], vb, pa0, pa1, pa2, pa3); pv_one<2>(o[2], vb, pa0, pa1, pa2, pa3); pv_one<3>(o[3], vb, pa0, pa1, pa2, pa3);
; __device__ __forceinline__ void attn_unit_dma(const bf16_t* __restrict__ Qb, const bf16_t* __restrict__ Kh, const bf16_t* __restrict__ Vh, int seq, char* lds, LAS unsigned char* ldsl, ...
;     ...
;   f32x16 pA0, pA1, pB0, pB1; bf16x8 pa0, pa1, pa2, pa3; const int NT = seq / KVBLK;
;   KDMA(0, 0); VDMA(0, 0); KDMA(1, 1);
;   int st = 0;
;   TOP(0, st);
;   qkt12(pA0, pA1, lds + DMA_KRING + st * SHM_K, qr, kb); partialSM_fix(pA0, pA1);
;   for (int j = 1; j + 1 < NT; j += 2) {
;     int sp = st; st = NEXT3(st);
;     TOP(j, st);
;     SBAR(); qkt12(pB0, pB1, lds + DMA_KRING + st * SHM_K, qr, kb);
;     finishSM_fix(pA0, pA1, l_reg, pa0, pa1, pa2, pa3); SBAR();
;     pv_d0(o, vb0 + sp * SHM_V, pa0, pa1, pa2, pa3); partialSM_fix(pB0, pB1);
;     sp = st; st = NEXT3(st);
;     TOP(j + 1, st);
	v_mfma_f32_32x32x16_bf16 v[212:227], v[176:179], v[152:155], v[212:227]
	ds_read_b128 v[172:175], v189 offset:256
	ds_read_b128 v[176:179], v189 offset:12544
	ds_read_b64_tr_b16 v[232:233], v191 offset:4096
	ds_read_b64_tr_b16 v[234:235], v191 offset:6144
	v_cvt_pk_bf16_f32 v70, v74, v75
	v_add_f32_e32 v196, v76, v196
	v_add_f32_e32 v197, v77, v197
	s_waitcnt lgkmcnt(7)
	v_mfma_f32_32x32x16_bf16 v[98:113], v[200:203], v[148:151], v[98:113]
	ds_read_b64_tr_b16 v[236:237], v191 offset:8192
	ds_read_b64_tr_b16 v[238:239], v191 offset:10240
	s_mov_b64 s[22:23], 0x61e0c180
	s_add_i32 m0, s11, 0x400
	v_lshl_add_u64 v[192:193], v[164:165], 0, s[22:23]
	global_load_lds_dwordx4 v[192:193], off
	v_cvt_pk_bf16_f32 v71, v76, v77
	v_add_f32_e32 v196, v78, v196
	v_add_f32_e32 v197, v79, v197
	v_cvt_pk_bf16_f32 v72, v78, v79
	s_waitcnt lgkmcnt(8)
	v_mfma_f32_32x32x16_bf16 v[212:227], v[204:207], v[148:151], v[212:227]
	ds_read_b128 v[200:203], v190 offset:256
	ds_read_b128 v[204:207], v190 offset:12544
	ds_read_b64_tr_b16 v[240:241], v191 offset:12288
	ds_read_b64_tr_b16 v[242:243], v191 offset:14336
	v_add_f32_e32 v196, v80, v196
	v_add_f32_e32 v197, v81, v197
	v_cvt_pk_bf16_f32 v73, v80, v81
	s_waitcnt lgkmcnt(9)
	v_mfma_f32_32x32x16_bf16 v[98:113], v[172:175], v[160:163], v[98:113]
	ds_read_b64_tr_b16 v[246:247], v191 offset:512
	ds_read_b64_tr_b16 v[248:249], v191 offset:2560
	v_add_f32_e32 v196, v196, v197
	s_nop 0
	v_permlane32_swap_b32_e32 v66, v68
	v_permlane32_swap_b32_e32 v67, v69
	s_waitcnt lgkmcnt(10)
	v_mfma_f32_32x32x16_bf16 v[212:227], v[176:179], v[160:163], v[212:227]
	ds_read_b64_tr_b16 v[250:251], v191 offset:4608
	ds_read_b64_tr_b16 v[252:253], v191 offset:6656
	v_permlane32_swap_b32_e32 v70, v72
	v_permlane32_swap_b32_e32 v71, v73
	v_add_f32_e32 v114, v114, v196
	s_waitcnt lgkmcnt(7)
	v_mfma_f32_32x32x16_bf16 v[98:113], v[200:203], v[156:159], v[98:113]
	s_waitcnt lgkmcnt(6)
	v_mfma_f32_32x32x16_bf16 v[212:227], v[204:207], v[156:159], v[212:227]
	v_mfma_f32_32x32x16_bf16 v[2:17], v[82:85], v[228:231], v[2:17]
	ds_read_b64_tr_b16 v[228:229], v191 offset:8704
	ds_read_b64_tr_b16 v[230:231], v191 offset:10752
	v_mfma_f32_32x32x16_bf16 v[2:17], v[86:89], v[232:235], v[2:17]
	ds_read_b64_tr_b16 v[232:233], v191 offset:12800
	ds_read_b64_tr_b16 v[234:235], v191 offset:14848
	v_mfma_f32_32x32x16_bf16 v[2:17], v[66:69], v[236:239], v[2:17]
	ds_read_b64_tr_b16 v[236:237], v191 offset:1024
	ds_read_b64_tr_b16 v[238:239], v191 offset:3072
	s_waitcnt lgkmcnt(10)
	v_mfma_f32_32x32x16_bf16 v[2:17], v[70:73], v[240:243], v[2:17]
	ds_read_b64_tr_b16 v[240:241], v191 offset:5120
	ds_read_b64_tr_b16 v[242:243], v191 offset:7168
	v_exp_f32_e32 v98, v98
	s_waitcnt lgkmcnt(10)
	v_mfma_f32_32x32x16_bf16 v[18:33], v[82:85], v[246:249], v[18:33]
	ds_read_b64_tr_b16 v[246:247], v191 offset:9216
	ds_read_b64_tr_b16 v[248:249], v191 offset:11264
	v_exp_f32_e32 v99, v99
	s_waitcnt lgkmcnt(10)
	v_mfma_f32_32x32x16_bf16 v[18:33], v[86:89], v[250:253], v[18:33]
	ds_read_b64_tr_b16 v[250:251], v191 offset:13312
	ds_read_b64_tr_b16 v[252:253], v191 offset:15360
	v_exp_f32_e32 v100, v100
	s_waitcnt lgkmcnt(10)
	v_mfma_f32_32x32x16_bf16 v[18:33], v[66:69], v[228:231], v[18:33]
	ds_read_b64_tr_b16 v[228:229], v191 offset:1536
	ds_read_b64_tr_b16 v[230:231], v191 offset:3584
	v_exp_f32_e32 v101, v101
	s_waitcnt lgkmcnt(10)
	v_mfma_f32_32x32x16_bf16 v[18:33], v[70:73], v[232:235], v[18:33]
	ds_read_b64_tr_b16 v[232:233], v191 offset:5632
	ds_read_b64_tr_b16 v[234:235], v191 offset:7680
	v_exp_f32_e32 v102, v102
	s_waitcnt lgkmcnt(10)
	v_mfma_f32_32x32x16_bf16 v[34:49], v[82:85], v[236:239], v[34:49]
	ds_read_b64_tr_b16 v[236:237], v191 offset:9728
	ds_read_b64_tr_b16 v[238:239], v191 offset:11776
	v_exp_f32_e32 v103, v103
	s_waitcnt lgkmcnt(10)
	v_mfma_f32_32x32x16_bf16 v[34:49], v[86:89], v[240:243], v[34:49]
	ds_read_b64_tr_b16 v[240:241], v191 offset:13824
	ds_read_b64_tr_b16 v[242:243], v191 offset:15872
	v_exp_f32_e32 v104, v104
	s_waitcnt lgkmcnt(10)
	v_mfma_f32_32x32x16_bf16 v[34:49], v[66:69], v[246:249], v[34:49]
	v_exp_f32_e32 v105, v105
	s_waitcnt lgkmcnt(8)
	v_mfma_f32_32x32x16_bf16 v[34:49], v[70:73], v[250:253], v[34:49]
	v_exp_f32_e32 v106, v106
	s_waitcnt lgkmcnt(6)
	v_mfma_f32_32x32x16_bf16 v[50:65], v[82:85], v[228:231], v[50:65]
	v_exp_f32_e32 v107, v107
	v_exp_f32_e32 v108, v108
	s_mul_i32 s6, s25, 0x6000
	s_mul_i32 s10, s24, 0x6000
	s_lshl_b32 s11, s26, 14
	s_waitcnt lgkmcnt(4)
	v_mfma_f32_32x32x16_bf16 v[50:65], v[86:89], v[232:235], v[50:65]
	v_exp_f32_e32 v109, v109
	v_exp_f32_e32 v110, v110
	s_add_i32 s10, s43, s10
	s_add_i32 s11, s52, s11
	v_add_u32_e32 v187, s6, v183
	s_waitcnt lgkmcnt(2)
	v_mfma_f32_32x32x16_bf16 v[50:65], v[66:69], v[236:239], v[50:65]
	v_exp_f32_e32 v111, v111
	v_exp_f32_e32 v112, v112
	v_add_u32_e32 v188, s6, v184
	v_add_u32_e32 v189, s6, v185
	v_add_u32_e32 v190, s6, v186
	s_waitcnt lgkmcnt(0)
	v_mfma_f32_32x32x16_bf16 v[50:65], v[70:73], v[240:243], v[50:65]
	v_exp_f32_e32 v113, v113
	v_lshl_add_u32 v191, s24, 14, v182
	s_waitcnt vmcnt(5)
	s_barrier
; __device__ __forceinline__ void finishSM_fix(f32x16& p0, f32x16& p1, float& l_lane, bf16x8& pa0, bf16x8& pa1, bf16x8& pa2, bf16x8& pa3) {
; #pragma unroll
;   for (int r = 0; r < 16; ++r) p1[r] = __builtin_amdgcn_exp2f(p1[r]);
;   float ps = 0;
; #pragma unroll
;   for (int r = 0; r < 16; ++r) ps += p0[r];
; #pragma unroll
;   for (int r = 0; r < 16; ++r) ps += p1[r];
;   l_lane += ps;
;     ...
;   PK4(p0, 0, pa0); PK4(p0, 8, pa1); PK4(p1, 0, pa2); PK4(p1, 8, pa3);
;     ...
; }
; __device__ __forceinline__ void qkt12(f32x16& p0, f32x16& p1, const char* Ks, const bf16x8 (&qr)[12], const int (&kb)[4]) {
;   p0 = f32x16{}; p1 = f32x16{};
;     ...
;   bf16x8 c0 = KLD(0, 0), c1 = KLD(0, 1);
; #pragma unroll
;   for (int d0 = 0; d0 < 12; ++d0) {
;     bf16x8 n0 = c0, n1 = c1;
;     if (d0 < 11) { n0 = KLD(d0 + 1, 0); n1 = KLD(d0 + 1, 1); }
;     __builtin_amdgcn_sched_group_barrier(0x100, 2, 0);
;     p0 = __builtin_amdgcn_mfma_f32_32x32x16_bf16(c0, qr[d0], p0, 0, 0, 0);
;     p1 = __builtin_amdgcn_mfma_f32_32x32x16_bf16(c1, qr[d0], p1, 0, 0, 0);
;     __builtin_amdgcn_sched_group_barrier(0x008, 2, 0);
;     c0 = n0; c1 = n1; }
;     ...
; }
	ds_read_b128 v[172:175], v187
	ds_read_b128 v[176:179], v187 offset:12288
	ds_read_b128 v[200:203], v188
	ds_read_b128 v[204:207], v188 offset:12288
	v_add_f32_e32 v196, v98, v99
	v_cvt_pk_bf16_f32 v98, v98, v99
	v_add_f32_e32 v197, v100, v101
	v_exp_f32_e32 v212, v212
	v_exp_f32_e32 v213, v213
	v_cvt_pk_bf16_f32 v99, v100, v101
	v_add_f32_e32 v196, v102, v196
	v_add_f32_e32 v197, v103, v197
	s_waitcnt lgkmcnt(3)
	v_mfma_f32_32x32x16_bf16 v[82:97], v[172:175], v[116:119], 0
	v_exp_f32_e32 v214, v214
	v_exp_f32_e32 v215, v215
	s_waitcnt lgkmcnt(2)
	v_mfma_f32_32x32x16_bf16 v[66:81], v[176:179], v[116:119], 0
	ds_read_b128 v[172:175], v189
	ds_read_b128 v[176:179], v189 offset:12288
	v_cvt_pk_bf16_f32 v100, v102, v103
	v_add_f32_e32 v196, v104, v196
	v_add_f32_e32 v197, v105, v197
	v_exp_f32_e32 v216, v216
	s_waitcnt lgkmcnt(3)
	v_mfma_f32_32x32x16_bf16 v[82:97], v[200:203], v[120:123], v[82:97]
	s_mov_b32 m0, s10
	v_lshl_add_u64 v[192:193], v[166:167], 0, s[94:95]
	global_load_lds_dwordx4 v[192:193], off
	v_exp_f32_e32 v217, v217
	s_waitcnt lgkmcnt(2)
	v_mfma_f32_32x32x16_bf16 v[66:81], v[204:207], v[120:123], v[66:81]
	ds_read_b128 v[200:203], v190
	ds_read_b128 v[204:207], v190 offset:12288
	v_cvt_pk_bf16_f32 v101, v104, v105
	v_add_f32_e32 v196, v106, v196
	v_add_f32_e32 v197, v107, v197
	v_exp_f32_e32 v218, v218
	s_waitcnt lgkmcnt(3)
	v_mfma_f32_32x32x16_bf16 v[82:97], v[172:175], v[124:127], v[82:97]
	v_exp_f32_e32 v219, v219
	s_waitcnt lgkmcnt(2)
	v_mfma_f32_32x32x16_bf16 v[66:81], v[176:179], v[124:127], v[66:81]
	ds_read_b128 v[172:175], v187 offset:128
	ds_read_b128 v[176:179], v187 offset:12416
	v_cvt_pk_bf16_f32 v102, v106, v107
	v_add_f32_e32 v196, v108, v196
	v_add_f32_e32 v197, v109, v197
	v_exp_f32_e32 v220, v220
	s_waitcnt lgkmcnt(3)
	v_mfma_f32_32x32x16_bf16 v[82:97], v[200:203], v[128:131], v[82:97]
	s_add_i32 m0, s10, 0x400
	v_lshl_add_u64 v[192:193], v[168:169], 0, s[94:95]
	global_load_lds_dwordx4 v[192:193], off
	v_exp_f32_e32 v221, v221
	v_cvt_pk_bf16_f32 v103, v108, v109
	s_waitcnt lgkmcnt(2)
	v_mfma_f32_32x32x16_bf16 v[66:81], v[204:207], v[128:131], v[66:81]
	ds_read_b128 v[200:203], v188 offset:128
	ds_read_b128 v[204:207], v188 offset:12416
	v_add_f32_e32 v196, v110, v196
	v_add_f32_e32 v197, v111, v197
	v_exp_f32_e32 v222, v222
	s_waitcnt lgkmcnt(3)
	v_mfma_f32_32x32x16_bf16 v[82:97], v[172:175], v[132:135], v[82:97]
	v_exp_f32_e32 v223, v223
	v_cvt_pk_bf16_f32 v104, v110, v111
	s_waitcnt lgkmcnt(2)
	v_mfma_f32_32x32x16_bf16 v[66:81], v[176:179], v[132:135], v[66:81]
	ds_read_b128 v[172:175], v189 offset:128
	ds_read_b128 v[176:179], v189 offset:12416
	v_add_f32_e32 v196, v112, v196
	v_add_f32_e32 v197, v113, v197
	v_exp_f32_e32 v224, v224
	s_waitcnt lgkmcnt(3)
	v_mfma_f32_32x32x16_bf16 v[82:97], v[200:203], v[136:139], v[82:97]
	s_add_i32 m0, s10, 0x800
	v_lshl_add_u64 v[192:193], v[170:171], 0, s[94:95]
	global_load_lds_dwordx4 v[192:193], off
	v_exp_f32_e32 v225, v225
	v_cvt_pk_bf16_f32 v105, v112, v113
	s_waitcnt lgkmcnt(2)
	v_mfma_f32_32x32x16_bf16 v[66:81], v[204:207], v[136:139], v[66:81]
	ds_read_b128 v[200:203], v190 offset:128
	ds_read_b128 v[204:207], v190 offset:12416
	v_exp_f32_e32 v226, v226
	v_exp_f32_e32 v227, v227
	s_waitcnt lgkmcnt(3)
	v_mfma_f32_32x32x16_bf16 v[82:97], v[172:175], v[140:143], v[82:97]
	v_add_f32_e32 v196, v212, v196
	v_add_f32_e32 v197, v213, v197
	v_cvt_pk_bf16_f32 v212, v212, v213
	s_waitcnt lgkmcnt(2)
	v_mfma_f32_32x32x16_bf16 v[66:81], v[176:179], v[140:143], v[66:81]
	ds_read_b128 v[172:175], v187 offset:256
	ds_read_b128 v[176:179], v187 offset:12544
	v_permlane32_swap_b32_e32 v98, v100
	v_permlane32_swap_b32_e32 v99, v101
	v_permlane32_swap_b32_e32 v102, v104
	v_permlane32_swap_b32_e32 v103, v105
	s_waitcnt lgkmcnt(3)
	v_mfma_f32_32x32x16_bf16 v[82:97], v[200:203], v[144:147], v[82:97]
	s_mov_b64 s[22:23], 0x61e8c100
	s_mov_b32 m0, s11
	v_lshl_add_u64 v[192:193], v[164:165], 0, s[22:23]
	global_load_lds_dwordx4 v[192:193], off
	v_add_f32_e32 v196, v214, v196
	v_add_f32_e32 v197, v215, v197
	v_cvt_pk_bf16_f32 v213, v214, v215
	s_waitcnt lgkmcnt(2)
	v_mfma_f32_32x32x16_bf16 v[66:81], v[204:207], v[144:147], v[66:81]
	ds_read_b128 v[200:203], v188 offset:256
	ds_read_b128 v[204:207], v188 offset:12544
	v_add_f32_e32 v196, v216, v196
	v_add_f32_e32 v197, v217, v197
	v_cvt_pk_bf16_f32 v214, v216, v217
	v_add_f32_e32 v196, v218, v196
	s_waitcnt lgkmcnt(3)
	v_mfma_f32_32x32x16_bf16 v[82:97], v[172:175], v[152:155], v[82:97]
	ds_read_b64_tr_b16 v[228:229], v191 offset:0
	ds_read_b64_tr_b16 v[230:231], v191 offset:2048
	v_add_f32_e32 v197, v219, v197
	v_cvt_pk_bf16_f32 v215, v218, v219
	v_add_f32_e32 v196, v220, v196
	v_add_f32_e32 v197, v221, v197
	s_waitcnt lgkmcnt(4)
	v_mfma_f32_32x32x16_bf16 v[66:81], v[176:179], v[152:155], v[66:81]
	ds_read_b128 v[172:175], v189 offset:256
	ds_read_b128 v[176:179], v189 offset:12544
	ds_read_b64_tr_b16 v[232:233], v191 offset:4096
	ds_read_b64_tr_b16 v[234:235], v191 offset:6144
	v_cvt_pk_bf16_f32 v216, v220, v221
	v_add_f32_e32 v196, v222, v196
	v_add_f32_e32 v197, v223, v197
	s_waitcnt lgkmcnt(7)
	v_mfma_f32_32x32x16_bf16 v[82:97], v[200:203], v[148:151], v[82:97]
	ds_read_b64_tr_b16 v[236:237], v191 offset:8192
	ds_read_b64_tr_b16 v[238:239], v191 offset:10240
	s_mov_b64 s[22:23], 0x61e8c180
	s_add_i32 m0, s11, 0x400
	v_lshl_add_u64 v[192:193], v[164:165], 0, s[22:23]
	global_load_lds_dwordx4 v[192:193], off
	v_cvt_pk_bf16_f32 v217, v222, v223
	v_add_f32_e32 v196, v224, v196
	v_add_f32_e32 v197, v225, v197
	v_cvt_pk_bf16_f32 v218, v224, v225
	s_waitcnt lgkmcnt(8)
; #define SBAR() __builtin_amdgcn_sched_barrier(0)
; template <int OFF> __device__ __forceinline__ s16x4 tr_read(int vb) {
;   s16x4 r; asm volatile("ds_read_b64_tr_b16 %0, %1 offset:%2" : "=&v"(r) : "v"(vb), "i"(OFF) : "memory"); return r;
; }
; template <int D0> __device__ __forceinline__ void pv_one(f32x16& od, int vb, bf16x8 pa0, bf16x8 pa1, bf16x8 pa2, bf16x8 pa3) {
;   const s16x4 l0 = tr_read<v_rd_off(D0, 0, 0)>(vb), h0 = tr_read<v_rd_off(D0, 0, 1)>(vb), l1 = tr_read<v_rd_off(D0, 1, 0)>(vb), h1 = tr_read<v_rd_off(D0, 1, 1)>(vb);
;   const s16x4 l2 = tr_read<v_rd_off(D0, 2, 0)>(vb), h2 = tr_read<v_rd_off(D0, 2, 1)>(vb), l3 = tr_read<v_rd_off(D0, 3, 0)>(vb), h3 = tr_read<v_rd_off(D0, 3, 1)>(vb);
;   asm volatile("s_waitcnt lgkmcnt(0)" ::: "memory"); SBAR();
;     ...
;   od = __builtin_amdgcn_mfma_f32_32x32x16_bf16(pa0, PK(l0, h0), od, 0, 0, 0);
;   od = __builtin_amdgcn_mfma_f32_32x32x16_bf16(pa1, PK(l1, h1), od, 0, 0, 0);
;   od = __builtin_amdgcn_mfma_f32_32x32x16_bf16(pa2, PK(l2, h2), od, 0, 0, 0);
;   od = __builtin_amdgcn_mfma_f32_32x32x16_bf16(pa3, PK(l3, h3), od, 0, 0, 0);
;     ...
; }
; __device__ __forceinline__ void pv_d0(f32x16 (&o)[4], int vb, bf16x8 pa0, bf16x8 pa1, bf16x8 pa2, bf16x8 pa3) {
;   pv_one<0>(o[0], vb, pa0, pa1, pa2, pa3); pv_one<1>(o[1], vb, pa0, pa1, pa2, pa3); pv_one<2>(o[2], vb, pa0, pa1, pa2, pa3); pv_one<3>(o[3], vb, pa0, pa1, pa2, pa3);
; }
; __device__ __forceinline__ void attn_unit_dma(const bf16_t* __restrict__ Qb, const bf16_t* __restrict__ Kh, const bf16_t* __restrict__ Vh, int seq, char* lds, LAS unsigned char* ldsl, ...
;     ...
;   for (int j = 1; j + 1 < NT; j += 2) {
;     int sp = st; st = NEXT3(st);
;     TOP(j, st);
;     SBAR(); qkt12(pB0, pB1, lds + DMA_KRING + st * SHM_K, qr, kb);
;     finishSM_fix(pA0, pA1, l_reg, pa0, pa1, pa2, pa3); SBAR();
;     pv_d0(o, vb0 + sp * SHM_V, pa0, pa1, pa2, pa3); partialSM_fix(pB0, pB1);
;     sp = st; st = NEXT3(st);
;     TOP(j + 1, st);
;     SBAR(); qkt12(pA0, pA1, lds + DMA_KRING + st * SHM_K, qr, kb);
;     finishSM_fix(pB0, pB1, l_reg, pa0, pa1, pa2, pa3); SBAR();
;     pv_d0(o, vb0 + sp * SHM_V, pa0, pa1, pa2, pa3); partialSM_fix(pA0, pA1);
;   }
	v_mfma_f32_32x32x16_bf16 v[66:81], v[204:207], v[148:151], v[66:81]
	ds_read_b128 v[200:203], v190 offset:256
	ds_read_b128 v[204:207], v190 offset:12544
	ds_read_b64_tr_b16 v[240:241], v191 offset:12288
	ds_read_b64_tr_b16 v[242:243], v191 offset:14336
	v_add_f32_e32 v196, v226, v196
	v_add_f32_e32 v197, v227, v197
	v_cvt_pk_bf16_f32 v219, v226, v227
	s_waitcnt lgkmcnt(9)
	v_mfma_f32_32x32x16_bf16 v[82:97], v[172:175], v[160:163], v[82:97]
	ds_read_b64_tr_b16 v[246:247], v191 offset:512
	ds_read_b64_tr_b16 v[248:249], v191 offset:2560
	v_add_f32_e32 v196, v196, v197
	s_nop 0
	v_permlane32_swap_b32_e32 v212, v214
	v_permlane32_swap_b32_e32 v213, v215
	s_waitcnt lgkmcnt(10)
	v_mfma_f32_32x32x16_bf16 v[66:81], v[176:179], v[160:163], v[66:81]
	ds_read_b64_tr_b16 v[250:251], v191 offset:4608
	ds_read_b64_tr_b16 v[252:253], v191 offset:6656
	v_permlane32_swap_b32_e32 v216, v218
	v_permlane32_swap_b32_e32 v217, v219
	v_add_f32_e32 v114, v114, v196
	s_waitcnt lgkmcnt(7)
	v_mfma_f32_32x32x16_bf16 v[82:97], v[200:203], v[156:159], v[82:97]
	s_waitcnt lgkmcnt(6)
	v_mfma_f32_32x32x16_bf16 v[66:81], v[204:207], v[156:159], v[66:81]
	v_mfma_f32_32x32x16_bf16 v[2:17], v[98:101], v[228:231], v[2:17]
	ds_read_b64_tr_b16 v[228:229], v191 offset:8704
	ds_read_b64_tr_b16 v[230:231], v191 offset:10752
	v_mfma_f32_32x32x16_bf16 v[2:17], v[102:105], v[232:235], v[2:17]
	ds_read_b64_tr_b16 v[232:233], v191 offset:12800
	ds_read_b64_tr_b16 v[234:235], v191 offset:14848
	v_mfma_f32_32x32x16_bf16 v[2:17], v[212:215], v[236:239], v[2:17]
	ds_read_b64_tr_b16 v[236:237], v191 offset:1024
	ds_read_b64_tr_b16 v[238:239], v191 offset:3072
	v_lshl_add_u64 v[166:167], v[166:167], 0, s[90:91]
	s_waitcnt lgkmcnt(10)
	v_mfma_f32_32x32x16_bf16 v[2:17], v[216:219], v[240:243], v[2:17]
	ds_read_b64_tr_b16 v[240:241], v191 offset:5120
	ds_read_b64_tr_b16 v[242:243], v191 offset:7168
	v_exp_f32_e32 v82, v82
	v_lshl_add_u64 v[168:169], v[168:169], 0, s[90:91]
	s_waitcnt lgkmcnt(10)
	v_mfma_f32_32x32x16_bf16 v[18:33], v[98:101], v[246:249], v[18:33]
	ds_read_b64_tr_b16 v[246:247], v191 offset:9216
	ds_read_b64_tr_b16 v[248:249], v191 offset:11264
	v_exp_f32_e32 v83, v83
	v_lshl_add_u64 v[170:171], v[170:171], 0, s[90:91]
	s_waitcnt lgkmcnt(10)
	v_mfma_f32_32x32x16_bf16 v[18:33], v[102:105], v[250:253], v[18:33]
	ds_read_b64_tr_b16 v[250:251], v191 offset:13312
	ds_read_b64_tr_b16 v[252:253], v191 offset:15360
	v_exp_f32_e32 v84, v84
	v_lshl_add_u64 v[164:165], v[164:165], 0, s[68:69]
	s_waitcnt lgkmcnt(10)
	v_mfma_f32_32x32x16_bf16 v[18:33], v[212:215], v[228:231], v[18:33]
	ds_read_b64_tr_b16 v[228:229], v191 offset:1536
	ds_read_b64_tr_b16 v[230:231], v191 offset:3584
	v_exp_f32_e32 v85, v85
	s_waitcnt lgkmcnt(10)
	v_mfma_f32_32x32x16_bf16 v[18:33], v[216:219], v[232:235], v[18:33]
	ds_read_b64_tr_b16 v[232:233], v191 offset:5632
	ds_read_b64_tr_b16 v[234:235], v191 offset:7680
	v_exp_f32_e32 v86, v86
	s_waitcnt lgkmcnt(10)
	v_mfma_f32_32x32x16_bf16 v[34:49], v[98:101], v[236:239], v[34:49]
	ds_read_b64_tr_b16 v[236:237], v191 offset:9728
	ds_read_b64_tr_b16 v[238:239], v191 offset:11776
	v_exp_f32_e32 v87, v87
	s_waitcnt lgkmcnt(10)
	v_mfma_f32_32x32x16_bf16 v[34:49], v[102:105], v[240:243], v[34:49]
	ds_read_b64_tr_b16 v[240:241], v191 offset:13824
	ds_read_b64_tr_b16 v[242:243], v191 offset:15872
	v_exp_f32_e32 v88, v88
	s_waitcnt lgkmcnt(10)
	v_mfma_f32_32x32x16_bf16 v[34:49], v[212:215], v[246:249], v[34:49]
	v_exp_f32_e32 v89, v89
	s_waitcnt lgkmcnt(8)
	v_mfma_f32_32x32x16_bf16 v[34:49], v[216:219], v[250:253], v[34:49]
	v_exp_f32_e32 v90, v90
	s_waitcnt lgkmcnt(6)
	v_mfma_f32_32x32x16_bf16 v[50:65], v[98:101], v[228:231], v[50:65]
	v_exp_f32_e32 v91, v91
	v_exp_f32_e32 v92, v92
	s_mov_b32 s26, s25
	s_add_i32 s22, s26, 1
	s_cmp_lg_u32 s26, 2
	s_cselect_b32 s24, s22, 0
	s_add_i32 s22, s24, 1
	s_waitcnt lgkmcnt(4)
	v_mfma_f32_32x32x16_bf16 v[50:65], v[102:105], v[232:235], v[50:65]
	v_exp_f32_e32 v93, v93
	v_exp_f32_e32 v94, v94
	s_cmp_lg_u32 s24, 2
	s_cselect_b32 s25, s22, 0
	s_mul_i32 s6, s24, 0x6000
	s_mul_i32 s10, s26, 0x6000
	s_lshl_b32 s11, s25, 14
	s_waitcnt lgkmcnt(2)
	v_mfma_f32_32x32x16_bf16 v[50:65], v[212:215], v[236:239], v[50:65]
	v_exp_f32_e32 v95, v95
	v_exp_f32_e32 v96, v96
	s_add_i32 s10, s43, s10
	s_add_i32 s11, s52, s11
	v_add_u32_e32 v187, s6, v183
	v_add_u32_e32 v188, s6, v184
	v_add_u32_e32 v189, s6, v185
	s_waitcnt lgkmcnt(0)
	v_mfma_f32_32x32x16_bf16 v[50:65], v[216:219], v[240:243], v[50:65]
	v_exp_f32_e32 v97, v97
	v_add_u32_e32 v190, s6, v186
	v_lshl_add_u32 v191, s26, 14, v182
	s_add_i32 s72, s72, 2
	s_cmp_lt_u32 s72, s37
	s_cbranch_scc1 .Lfa_loop
	v_mov_b32_e32 v195, v82
	v_mov_b32_e32 v216, v83
	v_mov_b32_e32 v213, v84
	v_mov_b32_e32 v215, v85
	v_mov_b32_e32 v197, v86
	v_mov_b32_e32 v214, v87
	v_mov_b32_e32 v196, v88
	v_mov_b32_e32 v212, v89
	v_mov_b32_e32 v191, v90
	v_mov_b32_e32 v193, v91
	v_mov_b32_e32 v189, v92
	v_mov_b32_e32 v192, v93
	v_mov_b32_e32 v188, v94
	v_mov_b32_e32 v190, v95
	v_mov_b32_e32 v187, v96
	v_mov_b32_e32 v194, v97
	s_branch .LBB0_853
	s_nop 0
	s_nop 0
	s_nop 0
	s_nop 0
	s_nop 0
	s_nop 0
	s_nop 0
	s_nop 0
